# v41 + mLSTM prep conv: both halves' row loads issued before compute (renamed register set for half 0): one round trip per pass instead of two
# baseline (speedup 1.0000x reference)
.LBB0_338:
	v_or_b32_e32 v205, s0, v155
	v_add_u32_e32 v204, s0, v156
	v_cmp_lt_i32_e32 vcc, 2, v205
	v_mov_b32_e32 v184, 0
	v_mov_b32_e32 v185, 0
	v_mov_b32_e32 v186, 0
	v_mov_b32_e32 v187, 0
	s_and_saveexec_b64 s[8:9], vcc
	s_cbranch_execz .LBB0_340_la
	v_mad_i64_i32 v[184:185], s[2:3], v204, s90, v[106:107]
	global_load_dwordx4 v[184:187], v[184:185], off nt
.LBB0_340_la:
	s_or_b64 exec, exec, s[8:9]
	v_cmp_lt_i32_e32 vcc, 1, v205
	v_mov_b32_e32 v188, 0
	v_mov_b32_e32 v192, 0
	v_mov_b32_e32 v193, 0
	v_mov_b32_e32 v194, 0
	v_mov_b32_e32 v195, 0
	s_and_saveexec_b64 s[8:9], vcc
	s_cbranch_execz .LBB0_342_la
	v_add_u32_e32 v189, 1, v204
	v_mad_i64_i32 v[190:191], s[2:3], v189, s90, v[106:107]
	global_load_dwordx4 v[192:195], v[190:191], off nt
.LBB0_342_la:
	s_or_b64 exec, exec, s[8:9]
	v_cmp_lt_i32_e32 vcc, 0, v205
	v_mov_b32_e32 v189, 0
	v_mov_b32_e32 v190, 0
	v_mov_b32_e32 v191, 0
	s_and_saveexec_b64 s[8:9], vcc
	s_cbranch_execz .LBB0_344_la
	v_or_b32_e32 v188, 2, v204
	v_mad_i64_i32 v[188:189], s[2:3], v188, s90, v[106:107]
	global_load_dwordx4 v[188:191], v[188:189], off nt
.LBB0_344_la:
	s_or_b64 exec, exec, s[8:9]
	v_mov_b32_e32 v200, 0
	v_mov_b32_e32 v196, 0
	v_mov_b32_e32 v197, 0
	v_mov_b32_e32 v198, 0
	v_mov_b32_e32 v199, 0
	s_and_saveexec_b64 s[8:9], s[6:7]
	s_cbranch_execz .LBB0_346_la
	v_add_u32_e32 v196, 3, v204
	v_mad_i64_i32 v[196:197], s[2:3], v196, s90, v[106:107]
	global_load_dwordx4 v[196:199], v[196:197], off nt
.LBB0_346_la:
	s_or_b64 exec, exec, s[8:9]
	v_mov_b32_e32 v201, 0
	v_mov_b32_e32 v202, 0
	v_mov_b32_e32 v203, 0
	s_and_saveexec_b64 s[8:9], s[6:7]
	s_cbranch_execz .LBB0_348_la
	v_add_u32_e32 v200, 4, v204
	v_mad_i64_i32 v[200:201], s[2:3], v200, s90, v[106:107]
	global_load_dwordx4 v[200:203], v[200:201], off nt
.LBB0_348_la:
	s_or_b64 exec, exec, s[8:9]
	v_mov_b32_e32 v224, 0
	v_mov_b32_e32 v228, 0
	v_mov_b32_e32 v229, 0
	v_mov_b32_e32 v230, 0
	v_mov_b32_e32 v231, 0
	s_and_saveexec_b64 s[8:9], s[6:7]
	s_cbranch_execz .LBB0_350_la
	v_add_u32_e32 v206, 5, v204
	v_mad_i64_i32 v[206:207], s[2:3], v206, s90, v[106:107]
	global_load_dwordx4 v[228:231], v[206:207], off nt
.LBB0_350_la:
	s_or_b64 exec, exec, s[8:9]
	v_mov_b32_e32 v225, 0
	v_mov_b32_e32 v226, 0
	v_mov_b32_e32 v227, 0
	s_and_saveexec_b64 s[8:9], s[6:7]
	s_cbranch_execz .LBB0_352_la
	v_add_u32_e32 v206, 6, v204
	v_mad_i64_i32 v[206:207], s[2:3], v206, s90, v[106:107]
	global_load_dwordx4 v[224:227], v[206:207], off nt
.LBB0_352_la:
	s_or_b64 exec, exec, s[8:9]
	v_mov_b32_e32 v216, 0
	v_mov_b32_e32 v220, 0
	v_mov_b32_e32 v221, 0
	v_mov_b32_e32 v222, 0
	v_mov_b32_e32 v223, 0
	s_and_saveexec_b64 s[8:9], s[6:7]
	s_cbranch_execz .LBB0_354_la
	v_add_u32_e32 v206, 7, v204
	v_mad_i64_i32 v[206:207], s[2:3], v206, s90, v[106:107]
	global_load_dwordx4 v[220:223], v[206:207], off nt
.LBB0_354_la:
	s_or_b64 exec, exec, s[8:9]
	v_cmp_lt_i32_e32 vcc, -6, v205
	v_mov_b32_e32 v217, 0
	v_mov_b32_e32 v218, 0
	v_mov_b32_e32 v219, 0
	s_and_saveexec_b64 s[8:9], vcc
	s_cbranch_execz .LBB0_356_la
	v_add_u32_e32 v206, 8, v204
	v_mad_i64_i32 v[206:207], s[2:3], v206, s90, v[106:107]
	global_load_dwordx4 v[216:219], v[206:207], off nt
.LBB0_356_la:
	s_or_b64 exec, exec, s[8:9]
	v_cmp_lt_i32_e32 vcc, -7, v205
	v_mov_b32_e32 v208, 0
	v_mov_b32_e32 v212, 0
	v_mov_b32_e32 v213, 0
	v_mov_b32_e32 v214, 0
	v_mov_b32_e32 v215, 0
	s_and_saveexec_b64 s[8:9], vcc
	s_cbranch_execz .LBB0_358_la
	v_add_u32_e32 v206, 9, v204
	v_mad_i64_i32 v[206:207], s[2:3], v206, s90, v[106:107]
	global_load_dwordx4 v[212:215], v[206:207], off nt
.LBB0_358_la:
	s_or_b64 exec, exec, s[8:9]
	v_cmp_lt_i32_e32 vcc, -8, v205
	v_mov_b32_e32 v209, 0
	v_mov_b32_e32 v210, 0
	v_mov_b32_e32 v211, 0
	s_and_saveexec_b64 s[8:9], vcc
	s_cbranch_execz .Lconv_l0end
	v_add_u32_e32 v204, 10, v204
	v_mad_i64_i32 v[204:205], s[2:3], v204, s90, v[106:107]
	global_load_dwordx4 v[208:211], v[204:205], off nt
.Lconv_l0end:
	s_or_b64 exec, exec, s[8:9]
	s_mov_b32 s0, 8
	v_or_b32_e32 v29, s0, v155
	v_add_u32_e32 v28, s0, v156
	v_cmp_lt_i32_e32 vcc, 2, v29
	v_mov_b32_e32 v8, 0
	v_mov_b32_e32 v9, 0
	v_mov_b32_e32 v10, 0
	v_mov_b32_e32 v11, 0
	s_and_saveexec_b64 s[8:9], vcc
	s_cbranch_execz .LBB0_340
	v_mad_i64_i32 v[8:9], s[2:3], v28, s90, v[106:107]
	global_load_dwordx4 v[8:11], v[8:9], off nt

.Lconv_l1end:
	s_mov_b32 s0, 0
.LBB0_360_ca:
	s_or_b64 exec, exec, s[8:9]
	s_waitcnt vmcnt(0)
	v_lshlrev_b32_e32 v134, 16, v188
	v_and_b32_e32 v135, 0xffff0000, v188
	v_lshlrev_b32_e32 v132, 16, v189
	v_and_b32_e32 v133, 0xffff0000, v189
	v_lshlrev_b32_e32 v188, 16, v184
	v_and_b32_e32 v189, 0xffff0000, v184
	v_lshlrev_b32_e32 v184, 16, v185
	v_and_b32_e32 v185, 0xffff0000, v185
	v_lshlrev_b32_e32 v116, 16, v193
	v_and_b32_e32 v117, 0xffff0000, v193
	v_pk_fma_f32 v[184:185], v[46:47], v[184:185], v[38:39]
	v_lshlrev_b32_e32 v110, 16, v197
	v_pk_fma_f32 v[184:185], v[66:67], v[116:117], v[184:185]
	v_and_b32_e32 v111, 0xffff0000, v197
	v_pk_fma_f32 v[184:185], v[58:59], v[132:133], v[184:185]
	v_lshlrev_b32_e32 v206, 16, v194
	v_pk_fma_f32 v[122:123], v[62:63], v[110:111], v[184:185]
	v_lshlrev_b32_e32 v184, 16, v186
	v_and_b32_e32 v185, 0xffff0000, v186
	v_and_b32_e32 v207, 0xffff0000, v194
	v_pk_fma_f32 v[184:185], v[40:41], v[184:185], v[32:33]
	v_lshlrev_b32_e32 v126, 16, v190
	v_and_b32_e32 v127, 0xffff0000, v190
	v_pk_fma_f32 v[184:185], v[48:49], v[206:207], v[184:185]
	v_lshlrev_b32_e32 v112, 16, v198
	v_and_b32_e32 v113, 0xffff0000, v198
	v_pk_fma_f32 v[184:185], v[52:53], v[126:127], v[184:185]
	v_lshlrev_b32_e32 v118, 16, v192
	v_pk_fma_f32 v[138:139], v[68:69], v[112:113], v[184:185]
	v_lshlrev_b32_e32 v184, 16, v187
	v_and_b32_e32 v185, 0xffff0000, v187
	v_and_b32_e32 v119, 0xffff0000, v192
	v_lshlrev_b32_e32 v204, 16, v195
	v_and_b32_e32 v205, 0xffff0000, v195
	v_pk_fma_f32 v[188:189], v[44:45], v[188:189], v[36:37]
	v_pk_fma_f32 v[184:185], v[42:43], v[184:185], v[34:35]
	v_lshlrev_b32_e32 v124, 16, v191
	v_and_b32_e32 v125, 0xffff0000, v191
	v_pk_fma_f32 v[188:189], v[64:65], v[118:119], v[188:189]
	v_pk_fma_f32 v[184:185], v[50:51], v[204:205], v[184:185]
	v_or_b32_e32 v128, s0, v154
	v_lshlrev_b32_e32 v108, 16, v196
	v_and_b32_e32 v109, 0xffff0000, v196
	v_pk_fma_f32 v[188:189], v[56:57], v[134:135], v[188:189]
	v_lshlrev_b32_e32 v114, 16, v199
	v_and_b32_e32 v115, 0xffff0000, v199
	v_pk_fma_f32 v[184:185], v[54:55], v[124:125], v[184:185]
	v_pk_fma_f32 v[120:121], v[60:61], v[108:109], v[188:189]
	v_pk_fma_f32 v[140:141], v[70:71], v[114:115], v[184:185]
	v_add_u32_e32 v136, s95, v128
	s_mov_b64 s[8:9], -1
	s_and_b64 vcc, exec, s[12:13]
	v_mul_f32_e32 v161, 0xbfb8aa3b, v120
	v_mul_f32_e32 v160, 0xbfb8aa3b, v121
	v_mul_f32_e32 v159, 0xbfb8aa3b, v122
	v_mul_f32_e32 v158, 0xbfb8aa3b, v123
	v_mul_f32_e32 v145, 0xbfb8aa3b, v138
	v_mul_f32_e32 v144, 0xbfb8aa3b, v139
	v_mul_f32_e32 v143, 0xbfb8aa3b, v140
	v_mul_f32_e32 v142, 0xbfb8aa3b, v141
	v_ashrrev_i32_e32 v137, 31, v136
	s_cbranch_vccz .LBB0_362_ca
	v_exp_f32_e32 v185, v161
	v_exp_f32_e32 v187, v160
	v_lshl_add_u32 v184, v128, 2, 0
	v_exp_f32_e32 v189, v158
	v_add_f32_e32 v185, 1.0, v185
	v_rcp_f32_e32 v186, v185
	v_exp_f32_e32 v185, v159
	v_add_f32_e32 v187, 1.0, v187
	v_add_u32_e32 v184, 0x21800, v184
	v_rcp_f32_e32 v187, v187
	ds_read_b32 v184, v184
	v_add_f32_e32 v185, 1.0, v185
	v_rcp_f32_e32 v188, v185
	v_add_f32_e32 v185, 1.0, v189
	v_rcp_f32_e32 v189, v185
	v_pk_mul_f32 v[186:187], v[120:121], v[186:187]
	v_exp_f32_e32 v195, v144
	v_pk_mul_f32 v[186:187], v[186:187], s[68:69] op_sel_hi:[1,0]
	v_pk_mul_f32 v[188:189], v[122:123], v[188:189]
	s_waitcnt lgkmcnt(0)
	v_pk_mul_f32 v[190:191], v[186:187], v[184:185] op_sel_hi:[1,0]
	v_exp_f32_e32 v185, v145
	v_pk_mul_f32 v[188:189], v[188:189], s[68:69] op_sel_hi:[1,0]
	v_exp_f32_e32 v197, v142
	v_add_f32_e32 v195, 1.0, v195
	v_pk_mul_f32 v[192:193], v[188:189], v[184:185] op_sel_hi:[1,0]
	v_add_f32_e32 v185, 1.0, v185
	v_rcp_f32_e32 v194, v185
	v_exp_f32_e32 v185, v143
	v_rcp_f32_e32 v195, v195
	s_mov_b64 s[8:9], 0
	v_add_f32_e32 v185, 1.0, v185
	v_rcp_f32_e32 v196, v185
	v_add_f32_e32 v185, 1.0, v197
	v_rcp_f32_e32 v197, v185
	v_pk_mul_f32 v[194:195], v[138:139], v[194:195]
	v_pk_mul_f32 v[196:197], v[140:141], v[196:197]
	v_pk_mul_f32 v[194:195], v[194:195], s[68:69] op_sel_hi:[1,0]
	v_pk_mul_f32 v[196:197], v[196:197], s[68:69] op_sel_hi:[1,0]
	v_pk_mul_f32 v[198:199], v[194:195], v[184:185] op_sel_hi:[1,0]
	v_pk_mul_f32 v[146:147], v[196:197], v[184:185] op_sel_hi:[1,0]
	v_cvt_pk_bf16_f32 v185, v188, v189
	v_lshlrev_b64 v[188:189], 11, v[136:137]
	v_cvt_pk_bf16_f32 v184, v186, v187
	v_cvt_pk_bf16_f32 v186, v194, v195
	v_cvt_pk_bf16_f32 v187, v196, v197
	v_lshl_add_u64 v[188:189], v[100:101], 0, v[188:189]
	global_store_dwordx4 v[188:189], v[184:187], off
	v_cvt_pk_bf16_f32 v188, v190, v191
	v_cvt_pk_bf16_f32 v189, v192, v193
	v_cvt_pk_bf16_f32 v190, v198, v199
	v_cvt_pk_bf16_f32 v191, v146, v147
	v_mad_u64_u32 v[184:185], s[0:1], v128, s91, v[102:103]
	ds_write_b128 v184, v[188:191]
	v_lshlrev_b32_e32 v184, 16, v188
	v_and_b32_e32 v185, 0xffff0000, v188
	v_lshlrev_b32_e32 v186, 16, v189
	v_and_b32_e32 v187, 0xffff0000, v189
	v_lshlrev_b32_e32 v188, 16, v190
	v_and_b32_e32 v189, 0xffff0000, v190
	v_lshlrev_b32_e32 v190, 16, v191
	v_and_b32_e32 v191, 0xffff0000, v191
	v_pk_add_f32 v[190:191], v[6:7], v[190:191]
	v_pk_add_f32 v[184:185], v[0:1], v[184:185]
	v_pk_add_f32 v[186:187], v[2:3], v[186:187]
	v_pk_add_f32 v[188:189], v[4:5], v[188:189]
	s_nop 0
	v_mov_b64_e32 v[198:199], v[190:191]
	v_mov_b64_e32 v[196:197], v[188:189]
	v_mov_b64_e32 v[194:195], v[186:187]
	v_mov_b64_e32 v[192:193], v[184:185]
.LBB0_362_ca:
	s_andn2_b64 vcc, exec, s[8:9]
	s_cbranch_vccnz .LBB0_364_ca
	v_exp_f32_e32 v184, v161
	v_exp_f32_e32 v185, v160
	v_exp_f32_e32 v186, v159
	v_exp_f32_e32 v187, v158
	v_exp_f32_e32 v188, v145
	v_exp_f32_e32 v189, v144
	v_exp_f32_e32 v190, v143
	v_exp_f32_e32 v191, v142
	v_add_f32_e32 v184, 1.0, v184
	v_add_f32_e32 v185, 1.0, v185
	v_add_f32_e32 v186, 1.0, v186
	v_add_f32_e32 v187, 1.0, v187
	v_add_f32_e32 v188, 1.0, v188
	v_add_f32_e32 v189, 1.0, v189
	v_rcp_f32_e32 v184, v184
	v_rcp_f32_e32 v185, v185
	v_rcp_f32_e32 v186, v186
	v_rcp_f32_e32 v187, v187
	v_rcp_f32_e32 v188, v188
	v_rcp_f32_e32 v189, v189
	v_add_f32_e32 v190, 1.0, v190
	v_add_f32_e32 v191, 1.0, v191
	v_rcp_f32_e32 v190, v190
	v_rcp_f32_e32 v191, v191
	v_pk_mul_f32 v[184:185], v[120:121], v[184:185]
	v_pk_mul_f32 v[186:187], v[122:123], v[186:187]
	v_pk_mul_f32 v[188:189], v[138:139], v[188:189]
	v_pk_mul_f32 v[190:191], v[140:141], v[190:191]
	v_cvt_pk_bf16_f32 v184, v184, v185
	v_cvt_pk_bf16_f32 v185, v186, v187
	v_cvt_pk_bf16_f32 v186, v188, v189
	v_lshlrev_b64 v[188:189], 11, v[136:137]
	v_cvt_pk_bf16_f32 v187, v190, v191
	v_lshl_add_u64 v[188:189], v[104:105], 0, v[188:189]
	v_mov_b64_e32 v[198:199], v[6:7]
	global_store_dwordx4 v[188:189], v[184:187], off
	v_mov_b64_e32 v[196:197], v[4:5]
	v_mov_b64_e32 v[194:195], v[2:3]
	v_mov_b64_e32 v[192:193], v[0:1]
	v_mov_b32_e32 v184, v0
	v_mov_b32_e32 v185, v1
	v_mov_b32_e32 v186, v2
	v_mov_b32_e32 v187, v3
	v_mov_b32_e32 v188, v4
	v_mov_b32_e32 v189, v5
	v_mov_b32_e32 v190, v6
	v_mov_b32_e32 v191, v7
.LBB0_364_ca:
	v_pk_fma_f32 v[0:1], v[44:45], v[118:119], v[36:37]
	v_lshlrev_b32_e32 v122, 16, v200
	v_pk_fma_f32 v[0:1], v[64:65], v[134:135], v[0:1]
	v_and_b32_e32 v123, 0xffff0000, v200
	v_pk_fma_f32 v[0:1], v[56:57], v[108:109], v[0:1]
	v_lshlrev_b32_e32 v120, 16, v201
	v_pk_fma_f32 v[136:137], v[60:61], v[122:123], v[0:1]
	v_pk_fma_f32 v[0:1], v[46:47], v[116:117], v[38:39]
	v_and_b32_e32 v121, 0xffff0000, v201
	v_pk_fma_f32 v[0:1], v[66:67], v[132:133], v[0:1]
	v_lshlrev_b32_e32 v118, 16, v202
	v_pk_fma_f32 v[0:1], v[58:59], v[110:111], v[0:1]
	v_and_b32_e32 v119, 0xffff0000, v202
	v_pk_fma_f32 v[140:141], v[62:63], v[120:121], v[0:1]
	v_pk_fma_f32 v[0:1], v[40:41], v[206:207], v[32:33]
	v_lshlrev_b32_e32 v116, 16, v203
	v_pk_fma_f32 v[0:1], v[48:49], v[126:127], v[0:1]
	v_and_b32_e32 v117, 0xffff0000, v203
	v_pk_fma_f32 v[0:1], v[52:53], v[112:113], v[0:1]
	s_mov_b64 s[16:17], -1
	v_pk_fma_f32 v[144:145], v[68:69], v[118:119], v[0:1]
	v_pk_fma_f32 v[0:1], v[42:43], v[204:205], v[34:35]
	s_andn2_b64 vcc, exec, s[12:13]
	v_pk_fma_f32 v[0:1], v[50:51], v[124:125], v[0:1]
	v_mul_f32_e32 v165, 0xbfb8aa3b, v136
	v_pk_fma_f32 v[0:1], v[54:55], v[114:115], v[0:1]
	v_mul_f32_e32 v164, 0xbfb8aa3b, v137
	v_pk_fma_f32 v[142:143], v[70:71], v[116:117], v[0:1]
	v_or_b32_e32 v0, 1, v128
	v_cndmask_b32_e64 v1, 0, 1, s[12:13]
	v_add_u32_e32 v138, s95, v0
	v_cmp_ne_u32_e64 s[8:9], 1, v1
	v_mul_f32_e32 v163, 0xbfb8aa3b, v140
	v_mul_f32_e32 v162, 0xbfb8aa3b, v141
	v_mul_f32_e32 v161, 0xbfb8aa3b, v144
	v_mul_f32_e32 v160, 0xbfb8aa3b, v145
	v_mul_f32_e32 v159, 0xbfb8aa3b, v142
	v_mul_f32_e32 v158, 0xbfb8aa3b, v143
	v_ashrrev_i32_e32 v139, 31, v138
	s_cbranch_vccnz .LBB0_366_ca
	v_exp_f32_e32 v3, v165
	v_lshl_add_u32 v1, v0, 2, 0
	v_add_u32_e32 v1, 0x21800, v1
	ds_read_b32 v2, v1
	v_exp_f32_e32 v1, v164
	v_add_f32_e32 v3, 1.0, v3
	v_rcp_f32_e32 v4, v3
	v_exp_f32_e32 v3, v163
	v_exp_f32_e32 v7, v162
	v_add_f32_e32 v1, 1.0, v1
	v_rcp_f32_e32 v5, v1
	v_add_f32_e32 v1, 1.0, v3
	v_rcp_f32_e32 v6, v1
	v_add_f32_e32 v1, 1.0, v7
	v_rcp_f32_e32 v7, v1
	v_exp_f32_e32 v1, v161
	v_pk_mul_f32 v[4:5], v[136:137], v[4:5]
	v_exp_f32_e32 v207, v158
	v_pk_mul_f32 v[6:7], v[140:141], v[6:7]
	v_add_f32_e32 v1, 1.0, v1
	v_pk_mul_f32 v[4:5], v[4:5], s[68:69] op_sel_hi:[1,0]
	v_pk_mul_f32 v[6:7], v[6:7], s[68:69] op_sel_hi:[1,0]
	v_rcp_f32_e32 v204, v1
	v_exp_f32_e32 v1, v159
	s_waitcnt lgkmcnt(0)
	v_pk_mul_f32 v[200:201], v[4:5], v[2:3] op_sel_hi:[1,0]
	v_pk_mul_f32 v[202:203], v[6:7], v[2:3] op_sel_hi:[1,0]
	v_exp_f32_e32 v3, v160
	v_add_f32_e32 v1, 1.0, v1
	v_rcp_f32_e32 v206, v1
	v_add_f32_e32 v1, 1.0, v207
	v_add_f32_e32 v3, 1.0, v3
	v_rcp_f32_e32 v205, v3
	v_rcp_f32_e32 v207, v1
	v_mad_u64_u32 v[0:1], s[0:1], v0, s91, v[102:103]
	v_pk_mul_f32 v[204:205], v[144:145], v[204:205]
	v_pk_mul_f32 v[206:207], v[142:143], v[206:207]
	v_pk_mul_f32 v[204:205], v[204:205], s[68:69] op_sel_hi:[1,0]
	v_pk_mul_f32 v[206:207], v[206:207], s[68:69] op_sel_hi:[1,0]
	v_pk_mul_f32 v[146:147], v[204:205], v[2:3] op_sel_hi:[1,0]
	v_pk_mul_f32 v[166:167], v[206:207], v[2:3] op_sel_hi:[1,0]
	v_cvt_pk_bf16_f32 v3, v6, v7
	v_lshlrev_b64 v[6:7], 11, v[138:139]
	v_cvt_pk_bf16_f32 v2, v4, v5
	v_cvt_pk_bf16_f32 v4, v204, v205
	v_cvt_pk_bf16_f32 v5, v206, v207
	v_lshl_add_u64 v[6:7], v[100:101], 0, v[6:7]
	global_store_dwordx4 v[6:7], v[2:5], off
	v_cvt_pk_bf16_f32 v6, v146, v147
	v_cvt_pk_bf16_f32 v7, v166, v167
	v_cvt_pk_bf16_f32 v4, v200, v201
	v_cvt_pk_bf16_f32 v5, v202, v203
	ds_write_b128 v0, v[4:7]
	v_lshlrev_b32_e32 v0, 16, v4
	v_and_b32_e32 v1, 0xffff0000, v4
	v_lshlrev_b32_e32 v2, 16, v5
	v_and_b32_e32 v3, 0xffff0000, v5
	v_lshlrev_b32_e32 v4, 16, v6
	v_and_b32_e32 v5, 0xffff0000, v6
	v_lshlrev_b32_e32 v6, 16, v7
	v_and_b32_e32 v7, 0xffff0000, v7
	v_pk_add_f32 v[6:7], v[198:199], v[6:7]
	v_pk_add_f32 v[0:1], v[192:193], v[0:1]
	v_pk_add_f32 v[2:3], v[194:195], v[2:3]
	v_pk_add_f32 v[4:5], v[196:197], v[4:5]
	s_mov_b64 s[16:17], 0
	v_mov_b64_e32 v[206:207], v[6:7]
	v_mov_b64_e32 v[204:205], v[4:5]
	v_mov_b64_e32 v[202:203], v[2:3]
	v_mov_b64_e32 v[200:201], v[0:1]
.LBB0_366_ca:
	s_andn2_b64 vcc, exec, s[16:17]
	s_cbranch_vccnz .LBB0_368_ca
	v_exp_f32_e32 v0, v165
	v_exp_f32_e32 v1, v164
	v_exp_f32_e32 v2, v163
	v_exp_f32_e32 v3, v162
	v_exp_f32_e32 v4, v161
	v_exp_f32_e32 v5, v160
	v_exp_f32_e32 v6, v159
	v_exp_f32_e32 v7, v158
	v_add_f32_e32 v0, 1.0, v0
	v_add_f32_e32 v1, 1.0, v1
	v_add_f32_e32 v2, 1.0, v2
	v_add_f32_e32 v3, 1.0, v3
	v_add_f32_e32 v4, 1.0, v4
	v_add_f32_e32 v5, 1.0, v5
	v_rcp_f32_e32 v0, v0
	v_rcp_f32_e32 v1, v1
	v_rcp_f32_e32 v2, v2
	v_rcp_f32_e32 v3, v3
	v_rcp_f32_e32 v4, v4
	v_rcp_f32_e32 v5, v5
	v_add_f32_e32 v6, 1.0, v6
	v_add_f32_e32 v7, 1.0, v7
	v_rcp_f32_e32 v6, v6
	v_rcp_f32_e32 v7, v7
	v_pk_mul_f32 v[0:1], v[136:137], v[0:1]
	v_pk_mul_f32 v[2:3], v[140:141], v[2:3]
	v_pk_mul_f32 v[4:5], v[144:145], v[4:5]
	v_pk_mul_f32 v[6:7], v[142:143], v[6:7]
	v_cvt_pk_bf16_f32 v0, v0, v1
	v_cvt_pk_bf16_f32 v1, v2, v3
	v_cvt_pk_bf16_f32 v2, v4, v5
	v_lshlrev_b64 v[4:5], 11, v[138:139]
	v_cvt_pk_bf16_f32 v3, v6, v7
	v_lshl_add_u64 v[4:5], v[104:105], 0, v[4:5]
	v_mov_b64_e32 v[206:207], v[198:199]
	global_store_dwordx4 v[4:5], v[0:3], off
	v_mov_b64_e32 v[204:205], v[196:197]
	v_mov_b64_e32 v[202:203], v[194:195]
	v_mov_b64_e32 v[200:201], v[192:193]
	v_mov_b32_e32 v0, v184
	v_mov_b32_e32 v1, v185
	v_mov_b32_e32 v2, v186
	v_mov_b32_e32 v3, v187
	v_mov_b32_e32 v4, v188
	v_mov_b32_e32 v5, v189
	v_mov_b32_e32 v6, v190
	v_mov_b32_e32 v7, v191
.LBB0_368_ca:
	v_pk_fma_f32 v[184:185], v[44:45], v[134:135], v[36:37]
	v_lshlrev_b32_e32 v136, 16, v228
	v_pk_fma_f32 v[184:185], v[64:65], v[108:109], v[184:185]
	v_and_b32_e32 v137, 0xffff0000, v228
	v_pk_fma_f32 v[184:185], v[56:57], v[122:123], v[184:185]
	v_lshlrev_b32_e32 v134, 16, v229
	v_pk_fma_f32 v[138:139], v[60:61], v[136:137], v[184:185]
	v_pk_fma_f32 v[184:185], v[46:47], v[132:133], v[38:39]
	v_and_b32_e32 v135, 0xffff0000, v229
	v_pk_fma_f32 v[184:185], v[66:67], v[110:111], v[184:185]
	v_lshlrev_b32_e32 v132, 16, v230
	v_pk_fma_f32 v[184:185], v[58:59], v[120:121], v[184:185]
	v_and_b32_e32 v133, 0xffff0000, v230
	v_pk_fma_f32 v[140:141], v[62:63], v[134:135], v[184:185]
	v_pk_fma_f32 v[184:185], v[40:41], v[126:127], v[32:33]
	v_lshlrev_b32_e32 v126, 16, v231
	v_pk_fma_f32 v[184:185], v[48:49], v[112:113], v[184:185]
	v_and_b32_e32 v127, 0xffff0000, v231
	v_pk_fma_f32 v[184:185], v[52:53], v[118:119], v[184:185]
	s_mov_b64 s[16:17], -1
	v_pk_fma_f32 v[142:143], v[68:69], v[132:133], v[184:185]
	v_pk_fma_f32 v[184:185], v[42:43], v[124:125], v[34:35]
	s_and_b64 vcc, exec, s[8:9]
	v_pk_fma_f32 v[184:185], v[50:51], v[114:115], v[184:185]
	v_mul_f32_e32 v161, 0xbfb8aa3b, v138
	v_pk_fma_f32 v[184:185], v[54:55], v[116:117], v[184:185]
	v_mul_f32_e32 v160, 0xbfb8aa3b, v139
	v_pk_fma_f32 v[230:231], v[70:71], v[126:127], v[184:185]
	v_or_b32_e32 v184, 2, v128
	v_add_u32_e32 v228, s95, v184
	v_mul_f32_e32 v159, 0xbfb8aa3b, v140
	v_mul_f32_e32 v158, 0xbfb8aa3b, v141
	v_mul_f32_e32 v145, 0xbfb8aa3b, v142
	v_mul_f32_e32 v144, 0xbfb8aa3b, v143
	v_mul_f32_e32 v125, 0xbfb8aa3b, v230
	v_mul_f32_e32 v124, 0xbfb8aa3b, v231
	v_ashrrev_i32_e32 v229, 31, v228
	s_cbranch_vccnz .LBB0_370_ca
	v_exp_f32_e32 v187, v161
	v_lshl_add_u32 v185, v184, 2, 0
	v_add_u32_e32 v185, 0x21800, v185
	ds_read_b32 v186, v185
	v_exp_f32_e32 v185, v160
	v_add_f32_e32 v187, 1.0, v187
	v_rcp_f32_e32 v188, v187
	v_exp_f32_e32 v187, v159
	v_exp_f32_e32 v191, v158
	v_add_f32_e32 v185, 1.0, v185
	v_rcp_f32_e32 v189, v185
	v_add_f32_e32 v185, 1.0, v187
	v_rcp_f32_e32 v190, v185
	v_add_f32_e32 v185, 1.0, v191
	v_rcp_f32_e32 v191, v185
	v_exp_f32_e32 v185, v145
	v_pk_mul_f32 v[188:189], v[138:139], v[188:189]
	v_exp_f32_e32 v199, v124
	v_pk_mul_f32 v[190:191], v[140:141], v[190:191]
	v_add_f32_e32 v185, 1.0, v185
	v_pk_mul_f32 v[188:189], v[188:189], s[68:69] op_sel_hi:[1,0]
	v_pk_mul_f32 v[190:191], v[190:191], s[68:69] op_sel_hi:[1,0]
	v_rcp_f32_e32 v196, v185
	v_exp_f32_e32 v185, v125
	s_waitcnt lgkmcnt(0)
	v_pk_mul_f32 v[192:193], v[188:189], v[186:187] op_sel_hi:[1,0]
	v_pk_mul_f32 v[194:195], v[190:191], v[186:187] op_sel_hi:[1,0]
	v_exp_f32_e32 v187, v144
	v_add_f32_e32 v185, 1.0, v185
	v_rcp_f32_e32 v198, v185
	v_add_f32_e32 v185, 1.0, v199
	v_add_f32_e32 v187, 1.0, v187
	v_rcp_f32_e32 v197, v187
	v_rcp_f32_e32 v199, v185
	v_mad_u64_u32 v[184:185], s[0:1], v184, s91, v[102:103]
	v_pk_mul_f32 v[196:197], v[142:143], v[196:197]
	v_pk_mul_f32 v[198:199], v[230:231], v[198:199]
	v_pk_mul_f32 v[196:197], v[196:197], s[68:69] op_sel_hi:[1,0]
	v_pk_mul_f32 v[198:199], v[198:199], s[68:69] op_sel_hi:[1,0]
	v_pk_mul_f32 v[146:147], v[196:197], v[186:187] op_sel_hi:[1,0]
	v_pk_mul_f32 v[162:163], v[198:199], v[186:187] op_sel_hi:[1,0]
	v_cvt_pk_bf16_f32 v187, v190, v191
	v_lshlrev_b64 v[190:191], 11, v[228:229]
	v_cvt_pk_bf16_f32 v186, v188, v189
	v_cvt_pk_bf16_f32 v188, v196, v197
	v_cvt_pk_bf16_f32 v189, v198, v199
	v_lshl_add_u64 v[190:191], v[100:101], 0, v[190:191]
	global_store_dwordx4 v[190:191], v[186:189], off
	v_cvt_pk_bf16_f32 v190, v146, v147
	v_cvt_pk_bf16_f32 v191, v162, v163
	v_cvt_pk_bf16_f32 v188, v192, v193
	v_cvt_pk_bf16_f32 v189, v194, v195
	ds_write_b128 v184, v[188:191]
	v_lshlrev_b32_e32 v184, 16, v188
	v_and_b32_e32 v185, 0xffff0000, v188
	v_lshlrev_b32_e32 v186, 16, v189
	v_and_b32_e32 v187, 0xffff0000, v189
	v_lshlrev_b32_e32 v188, 16, v190
	v_and_b32_e32 v189, 0xffff0000, v190
	v_lshlrev_b32_e32 v190, 16, v191
	v_and_b32_e32 v191, 0xffff0000, v191
	v_pk_add_f32 v[190:191], v[206:207], v[190:191]
	v_pk_add_f32 v[184:185], v[200:201], v[184:185]
	v_pk_add_f32 v[186:187], v[202:203], v[186:187]
	v_pk_add_f32 v[188:189], v[204:205], v[188:189]
	s_mov_b64 s[16:17], 0
	v_mov_b64_e32 v[198:199], v[190:191]
	v_mov_b64_e32 v[196:197], v[188:189]
	v_mov_b64_e32 v[194:195], v[186:187]
	v_mov_b64_e32 v[192:193], v[184:185]
.LBB0_370_ca:
	s_andn2_b64 vcc, exec, s[16:17]
	s_cbranch_vccnz .LBB0_372_ca
	v_exp_f32_e32 v184, v161
	v_exp_f32_e32 v185, v160
	v_exp_f32_e32 v186, v159
	v_exp_f32_e32 v187, v158
	v_exp_f32_e32 v188, v145
	v_exp_f32_e32 v189, v144
	v_exp_f32_e32 v190, v125
	v_exp_f32_e32 v191, v124
	v_add_f32_e32 v184, 1.0, v184
	v_add_f32_e32 v185, 1.0, v185
	v_add_f32_e32 v186, 1.0, v186
	v_add_f32_e32 v187, 1.0, v187
	v_add_f32_e32 v188, 1.0, v188
	v_add_f32_e32 v189, 1.0, v189
	v_rcp_f32_e32 v184, v184
	v_rcp_f32_e32 v185, v185
	v_rcp_f32_e32 v186, v186
	v_rcp_f32_e32 v187, v187
	v_rcp_f32_e32 v188, v188
	v_rcp_f32_e32 v189, v189
	v_add_f32_e32 v190, 1.0, v190
	v_add_f32_e32 v191, 1.0, v191
	v_rcp_f32_e32 v190, v190
	v_rcp_f32_e32 v191, v191
	v_pk_mul_f32 v[184:185], v[138:139], v[184:185]
	v_pk_mul_f32 v[186:187], v[140:141], v[186:187]
	v_pk_mul_f32 v[188:189], v[142:143], v[188:189]
	v_pk_mul_f32 v[190:191], v[230:231], v[190:191]
	v_cvt_pk_bf16_f32 v184, v184, v185
	v_cvt_pk_bf16_f32 v185, v186, v187
	v_cvt_pk_bf16_f32 v186, v188, v189
	v_lshlrev_b64 v[188:189], 11, v[228:229]
	v_cvt_pk_bf16_f32 v187, v190, v191
	v_lshl_add_u64 v[188:189], v[104:105], 0, v[188:189]
	v_mov_b64_e32 v[192:193], v[200:201]
	global_store_dwordx4 v[188:189], v[184:187], off
	v_mov_b64_e32 v[194:195], v[202:203]
	v_mov_b64_e32 v[196:197], v[204:205]
	v_mov_b64_e32 v[198:199], v[206:207]
	v_mov_b32_e32 v184, v0
	v_mov_b32_e32 v185, v1
	v_mov_b32_e32 v186, v2
	v_mov_b32_e32 v187, v3
	v_mov_b32_e32 v188, v4
	v_mov_b32_e32 v189, v5
	v_mov_b32_e32 v190, v6
	v_mov_b32_e32 v191, v7
.LBB0_372_ca:
	v_pk_fma_f32 v[0:1], v[44:45], v[108:109], v[36:37]
	v_lshlrev_b32_e32 v124, 16, v224
	v_pk_fma_f32 v[0:1], v[64:65], v[122:123], v[0:1]
	v_and_b32_e32 v125, 0xffff0000, v224
	v_pk_fma_f32 v[0:1], v[56:57], v[136:137], v[0:1]
	v_lshlrev_b32_e32 v230, 16, v225
	v_pk_fma_f32 v[108:109], v[60:61], v[124:125], v[0:1]
	v_pk_fma_f32 v[0:1], v[46:47], v[110:111], v[38:39]
	v_and_b32_e32 v231, 0xffff0000, v225
	v_pk_fma_f32 v[0:1], v[66:67], v[120:121], v[0:1]
	v_lshlrev_b32_e32 v228, 16, v226
	v_pk_fma_f32 v[0:1], v[58:59], v[134:135], v[0:1]
	v_and_b32_e32 v229, 0xffff0000, v226
	v_pk_fma_f32 v[110:111], v[62:63], v[230:231], v[0:1]
	v_pk_fma_f32 v[0:1], v[40:41], v[112:113], v[32:33]
	v_lshlrev_b32_e32 v224, 16, v227
	v_pk_fma_f32 v[0:1], v[48:49], v[118:119], v[0:1]
	v_and_b32_e32 v225, 0xffff0000, v227
	v_pk_fma_f32 v[0:1], v[52:53], v[132:133], v[0:1]
	s_mov_b64 s[16:17], -1
	v_pk_fma_f32 v[138:139], v[68:69], v[228:229], v[0:1]
	v_pk_fma_f32 v[0:1], v[42:43], v[114:115], v[34:35]
	s_and_b64 vcc, exec, s[8:9]
	v_pk_fma_f32 v[0:1], v[50:51], v[116:117], v[0:1]
	v_mul_f32_e32 v145, 0xbfb8aa3b, v108
	v_pk_fma_f32 v[0:1], v[54:55], v[126:127], v[0:1]
	v_mul_f32_e32 v144, 0xbfb8aa3b, v109
	v_pk_fma_f32 v[112:113], v[70:71], v[224:225], v[0:1]
	v_or_b32_e32 v0, 3, v128
	v_add_u32_e32 v226, s95, v0
	v_mul_f32_e32 v143, 0xbfb8aa3b, v110
	v_mul_f32_e32 v142, 0xbfb8aa3b, v111
	v_mul_f32_e32 v141, 0xbfb8aa3b, v138
	v_mul_f32_e32 v140, 0xbfb8aa3b, v139
	v_mul_f32_e32 v115, 0xbfb8aa3b, v112
	v_mul_f32_e32 v114, 0xbfb8aa3b, v113
	v_ashrrev_i32_e32 v227, 31, v226
	s_cbranch_vccnz .LBB0_374_ca
	v_exp_f32_e32 v3, v145
	v_lshl_add_u32 v1, v0, 2, 0
	v_add_u32_e32 v1, 0x21800, v1
	ds_read_b32 v2, v1
	v_exp_f32_e32 v1, v144
	v_add_f32_e32 v3, 1.0, v3
	v_rcp_f32_e32 v4, v3
	v_exp_f32_e32 v3, v143
	v_exp_f32_e32 v7, v142
	v_add_f32_e32 v1, 1.0, v1
	v_rcp_f32_e32 v5, v1
	v_add_f32_e32 v1, 1.0, v3
	v_rcp_f32_e32 v6, v1
	v_add_f32_e32 v1, 1.0, v7
	v_rcp_f32_e32 v7, v1
	v_exp_f32_e32 v1, v141
	v_pk_mul_f32 v[4:5], v[108:109], v[4:5]
	v_exp_f32_e32 v207, v114
	v_pk_mul_f32 v[6:7], v[110:111], v[6:7]
	v_add_f32_e32 v1, 1.0, v1
	v_pk_mul_f32 v[4:5], v[4:5], s[68:69] op_sel_hi:[1,0]
	v_pk_mul_f32 v[6:7], v[6:7], s[68:69] op_sel_hi:[1,0]
	v_rcp_f32_e32 v204, v1
	v_exp_f32_e32 v1, v115
	s_waitcnt lgkmcnt(0)
	v_pk_mul_f32 v[200:201], v[4:5], v[2:3] op_sel_hi:[1,0]
	v_pk_mul_f32 v[202:203], v[6:7], v[2:3] op_sel_hi:[1,0]
	v_exp_f32_e32 v3, v140
	v_add_f32_e32 v1, 1.0, v1
	v_rcp_f32_e32 v206, v1
	v_add_f32_e32 v1, 1.0, v207
	v_add_f32_e32 v3, 1.0, v3
	v_rcp_f32_e32 v205, v3
	v_rcp_f32_e32 v207, v1
	v_mad_u64_u32 v[0:1], s[0:1], v0, s91, v[102:103]
	v_pk_mul_f32 v[204:205], v[138:139], v[204:205]
	v_pk_mul_f32 v[206:207], v[112:113], v[206:207]
	v_pk_mul_f32 v[204:205], v[204:205], s[68:69] op_sel_hi:[1,0]
	v_pk_mul_f32 v[206:207], v[206:207], s[68:69] op_sel_hi:[1,0]
	v_pk_mul_f32 v[146:147], v[204:205], v[2:3] op_sel_hi:[1,0]
	v_pk_mul_f32 v[158:159], v[206:207], v[2:3] op_sel_hi:[1,0]
	v_cvt_pk_bf16_f32 v3, v6, v7
	v_lshlrev_b64 v[6:7], 11, v[226:227]
	v_cvt_pk_bf16_f32 v2, v4, v5
	v_cvt_pk_bf16_f32 v4, v204, v205
	v_cvt_pk_bf16_f32 v5, v206, v207
	v_lshl_add_u64 v[6:7], v[100:101], 0, v[6:7]
	global_store_dwordx4 v[6:7], v[2:5], off
	v_cvt_pk_bf16_f32 v6, v146, v147
	v_cvt_pk_bf16_f32 v7, v158, v159
	v_cvt_pk_bf16_f32 v4, v200, v201
	v_cvt_pk_bf16_f32 v5, v202, v203
	ds_write_b128 v0, v[4:7]
	v_lshlrev_b32_e32 v0, 16, v4
	v_and_b32_e32 v1, 0xffff0000, v4
	v_lshlrev_b32_e32 v2, 16, v5
	v_and_b32_e32 v3, 0xffff0000, v5
	v_lshlrev_b32_e32 v4, 16, v6
	v_and_b32_e32 v5, 0xffff0000, v6
	v_lshlrev_b32_e32 v6, 16, v7
	v_and_b32_e32 v7, 0xffff0000, v7
	v_pk_add_f32 v[6:7], v[198:199], v[6:7]
	v_pk_add_f32 v[0:1], v[192:193], v[0:1]
	v_pk_add_f32 v[2:3], v[194:195], v[2:3]
	v_pk_add_f32 v[4:5], v[196:197], v[4:5]
	s_mov_b64 s[16:17], 0
	v_mov_b64_e32 v[206:207], v[6:7]
	v_mov_b64_e32 v[204:205], v[4:5]
	v_mov_b64_e32 v[202:203], v[2:3]
	v_mov_b64_e32 v[200:201], v[0:1]
.LBB0_374_ca:
	s_andn2_b64 vcc, exec, s[16:17]
	s_cbranch_vccnz .LBB0_376_ca
	v_exp_f32_e32 v0, v145
	v_exp_f32_e32 v1, v144
	v_exp_f32_e32 v2, v143
	v_exp_f32_e32 v3, v142
	v_exp_f32_e32 v4, v141
	v_exp_f32_e32 v5, v140
	v_exp_f32_e32 v6, v115
	v_exp_f32_e32 v7, v114
	v_add_f32_e32 v0, 1.0, v0
	v_add_f32_e32 v1, 1.0, v1
	v_add_f32_e32 v2, 1.0, v2
	v_add_f32_e32 v3, 1.0, v3
	v_add_f32_e32 v4, 1.0, v4
	v_add_f32_e32 v5, 1.0, v5
	v_rcp_f32_e32 v0, v0
	v_rcp_f32_e32 v1, v1
	v_rcp_f32_e32 v2, v2
	v_rcp_f32_e32 v3, v3
	v_rcp_f32_e32 v4, v4
	v_rcp_f32_e32 v5, v5
	v_add_f32_e32 v6, 1.0, v6
	v_add_f32_e32 v7, 1.0, v7
	v_rcp_f32_e32 v6, v6
	v_rcp_f32_e32 v7, v7
	v_pk_mul_f32 v[0:1], v[108:109], v[0:1]
	v_pk_mul_f32 v[2:3], v[110:111], v[2:3]
	v_pk_mul_f32 v[4:5], v[138:139], v[4:5]
	v_pk_mul_f32 v[6:7], v[112:113], v[6:7]
	v_cvt_pk_bf16_f32 v0, v0, v1
	v_cvt_pk_bf16_f32 v1, v2, v3
	v_cvt_pk_bf16_f32 v2, v4, v5
	v_lshlrev_b64 v[4:5], 11, v[226:227]
	v_cvt_pk_bf16_f32 v3, v6, v7
	v_lshl_add_u64 v[4:5], v[104:105], 0, v[4:5]
	v_mov_b64_e32 v[206:207], v[198:199]
	global_store_dwordx4 v[4:5], v[0:3], off
	v_mov_b64_e32 v[204:205], v[196:197]
	v_mov_b64_e32 v[202:203], v[194:195]
	v_mov_b64_e32 v[200:201], v[192:193]
	v_mov_b32_e32 v0, v184
	v_mov_b32_e32 v1, v185
	v_mov_b32_e32 v2, v186
	v_mov_b32_e32 v3, v187
	v_mov_b32_e32 v4, v188
	v_mov_b32_e32 v5, v189
	v_mov_b32_e32 v6, v190
	v_mov_b32_e32 v7, v191
.LBB0_376_ca:
	v_pk_fma_f32 v[184:185], v[44:45], v[122:123], v[36:37]
	v_lshlrev_b32_e32 v110, 16, v220
	v_pk_fma_f32 v[184:185], v[64:65], v[136:137], v[184:185]
	v_and_b32_e32 v111, 0xffff0000, v220
	v_pk_fma_f32 v[184:185], v[56:57], v[124:125], v[184:185]
	v_lshlrev_b32_e32 v108, 16, v221
	v_pk_fma_f32 v[112:113], v[60:61], v[110:111], v[184:185]
	v_pk_fma_f32 v[184:185], v[46:47], v[120:121], v[38:39]
	v_and_b32_e32 v109, 0xffff0000, v221
	v_pk_fma_f32 v[184:185], v[66:67], v[134:135], v[184:185]
	v_lshlrev_b32_e32 v226, 16, v222
	v_pk_fma_f32 v[184:185], v[58:59], v[230:231], v[184:185]
	v_and_b32_e32 v227, 0xffff0000, v222
	v_pk_fma_f32 v[114:115], v[62:63], v[108:109], v[184:185]
	v_pk_fma_f32 v[184:185], v[40:41], v[118:119], v[32:33]
	v_lshlrev_b32_e32 v220, 16, v223
	v_pk_fma_f32 v[184:185], v[48:49], v[132:133], v[184:185]
	v_and_b32_e32 v221, 0xffff0000, v223
	v_pk_fma_f32 v[184:185], v[52:53], v[228:229], v[184:185]
	s_mov_b64 s[16:17], -1
	v_pk_fma_f32 v[118:119], v[68:69], v[226:227], v[184:185]
	v_pk_fma_f32 v[184:185], v[42:43], v[116:117], v[34:35]
	s_and_b64 vcc, exec, s[8:9]
	v_pk_fma_f32 v[184:185], v[50:51], v[126:127], v[184:185]
	v_mul_f32_e32 v141, 0xbfb8aa3b, v112
	v_pk_fma_f32 v[184:185], v[54:55], v[224:225], v[184:185]
	v_mul_f32_e32 v140, 0xbfb8aa3b, v113
	v_pk_fma_f32 v[116:117], v[70:71], v[220:221], v[184:185]
	v_or_b32_e32 v184, 4, v128
	v_add_u32_e32 v222, s95, v184
	v_mul_f32_e32 v139, 0xbfb8aa3b, v114
	v_mul_f32_e32 v138, 0xbfb8aa3b, v115
	v_mul_f32_e32 v123, 0xbfb8aa3b, v118
	v_mul_f32_e32 v122, 0xbfb8aa3b, v119
	v_mul_f32_e32 v121, 0xbfb8aa3b, v116
	v_mul_f32_e32 v120, 0xbfb8aa3b, v117
	v_ashrrev_i32_e32 v223, 31, v222
	s_cbranch_vccnz .LBB0_378_ca
	v_exp_f32_e32 v187, v141
	v_lshl_add_u32 v185, v184, 2, 0
	v_add_u32_e32 v185, 0x21800, v185
	ds_read_b32 v186, v185
	v_exp_f32_e32 v185, v140
	v_add_f32_e32 v187, 1.0, v187
	v_rcp_f32_e32 v188, v187
	v_exp_f32_e32 v187, v139
	v_exp_f32_e32 v191, v138
	v_add_f32_e32 v185, 1.0, v185
	v_rcp_f32_e32 v189, v185
	v_add_f32_e32 v185, 1.0, v187
	v_rcp_f32_e32 v190, v185
	v_add_f32_e32 v185, 1.0, v191
	v_rcp_f32_e32 v191, v185
	v_exp_f32_e32 v185, v123
	v_pk_mul_f32 v[188:189], v[112:113], v[188:189]
	v_exp_f32_e32 v199, v120
	v_pk_mul_f32 v[190:191], v[114:115], v[190:191]
	v_add_f32_e32 v185, 1.0, v185
	v_pk_mul_f32 v[188:189], v[188:189], s[68:69] op_sel_hi:[1,0]
	v_pk_mul_f32 v[190:191], v[190:191], s[68:69] op_sel_hi:[1,0]
	v_rcp_f32_e32 v196, v185
	v_exp_f32_e32 v185, v121
	s_waitcnt lgkmcnt(0)
	v_pk_mul_f32 v[192:193], v[188:189], v[186:187] op_sel_hi:[1,0]
	v_pk_mul_f32 v[194:195], v[190:191], v[186:187] op_sel_hi:[1,0]
	v_exp_f32_e32 v187, v122
	v_add_f32_e32 v185, 1.0, v185
	v_rcp_f32_e32 v198, v185
	v_add_f32_e32 v185, 1.0, v199
	v_add_f32_e32 v187, 1.0, v187
	v_rcp_f32_e32 v197, v187
	v_rcp_f32_e32 v199, v185
	v_mad_u64_u32 v[184:185], s[0:1], v184, s91, v[102:103]
	v_pk_mul_f32 v[196:197], v[118:119], v[196:197]
	v_pk_mul_f32 v[198:199], v[116:117], v[198:199]
	v_pk_mul_f32 v[196:197], v[196:197], s[68:69] op_sel_hi:[1,0]
	v_pk_mul_f32 v[198:199], v[198:199], s[68:69] op_sel_hi:[1,0]
	v_pk_mul_f32 v[142:143], v[196:197], v[186:187] op_sel_hi:[1,0]
	v_pk_mul_f32 v[144:145], v[198:199], v[186:187] op_sel_hi:[1,0]
	v_cvt_pk_bf16_f32 v187, v190, v191
	v_lshlrev_b64 v[190:191], 11, v[222:223]
	v_cvt_pk_bf16_f32 v186, v188, v189
	v_cvt_pk_bf16_f32 v188, v196, v197
	v_cvt_pk_bf16_f32 v189, v198, v199
	v_lshl_add_u64 v[190:191], v[100:101], 0, v[190:191]
	global_store_dwordx4 v[190:191], v[186:189], off
	v_cvt_pk_bf16_f32 v190, v142, v143
	v_cvt_pk_bf16_f32 v191, v144, v145
	v_cvt_pk_bf16_f32 v188, v192, v193
	v_cvt_pk_bf16_f32 v189, v194, v195
	ds_write_b128 v184, v[188:191]
	v_lshlrev_b32_e32 v184, 16, v188
	v_and_b32_e32 v185, 0xffff0000, v188
	v_lshlrev_b32_e32 v186, 16, v189
	v_and_b32_e32 v187, 0xffff0000, v189
	v_lshlrev_b32_e32 v188, 16, v190
	v_and_b32_e32 v189, 0xffff0000, v190
	v_lshlrev_b32_e32 v190, 16, v191
	v_and_b32_e32 v191, 0xffff0000, v191
	v_pk_add_f32 v[190:191], v[206:207], v[190:191]
	v_pk_add_f32 v[184:185], v[200:201], v[184:185]
	v_pk_add_f32 v[186:187], v[202:203], v[186:187]
	v_pk_add_f32 v[188:189], v[204:205], v[188:189]
	s_mov_b64 s[16:17], 0
	v_mov_b64_e32 v[198:199], v[190:191]
	v_mov_b64_e32 v[196:197], v[188:189]
	v_mov_b64_e32 v[194:195], v[186:187]
	v_mov_b64_e32 v[192:193], v[184:185]
.LBB0_378_ca:
	s_andn2_b64 vcc, exec, s[16:17]
	s_cbranch_vccnz .LBB0_380_ca
	v_exp_f32_e32 v184, v141
	v_exp_f32_e32 v185, v140
	v_exp_f32_e32 v186, v139
	v_exp_f32_e32 v187, v138
	v_exp_f32_e32 v188, v123
	v_exp_f32_e32 v189, v122
	v_exp_f32_e32 v190, v121
	v_exp_f32_e32 v191, v120
	v_add_f32_e32 v184, 1.0, v184
	v_add_f32_e32 v185, 1.0, v185
	v_add_f32_e32 v186, 1.0, v186
	v_add_f32_e32 v187, 1.0, v187
	v_add_f32_e32 v188, 1.0, v188
	v_add_f32_e32 v189, 1.0, v189
	v_rcp_f32_e32 v184, v184
	v_rcp_f32_e32 v185, v185
	v_rcp_f32_e32 v186, v186
	v_rcp_f32_e32 v187, v187
	v_rcp_f32_e32 v188, v188
	v_rcp_f32_e32 v189, v189
	v_add_f32_e32 v190, 1.0, v190
	v_add_f32_e32 v191, 1.0, v191
	v_rcp_f32_e32 v190, v190
	v_rcp_f32_e32 v191, v191
	v_pk_mul_f32 v[184:185], v[112:113], v[184:185]
	v_pk_mul_f32 v[186:187], v[114:115], v[186:187]
	v_pk_mul_f32 v[188:189], v[118:119], v[188:189]
	v_pk_mul_f32 v[190:191], v[116:117], v[190:191]
	v_cvt_pk_bf16_f32 v184, v184, v185
	v_cvt_pk_bf16_f32 v185, v186, v187
	v_cvt_pk_bf16_f32 v186, v188, v189
	v_lshlrev_b64 v[188:189], 11, v[222:223]
	v_cvt_pk_bf16_f32 v187, v190, v191
	v_lshl_add_u64 v[188:189], v[104:105], 0, v[188:189]
	v_mov_b64_e32 v[192:193], v[200:201]
	global_store_dwordx4 v[188:189], v[184:187], off
	v_mov_b64_e32 v[194:195], v[202:203]
	v_mov_b64_e32 v[196:197], v[204:205]
	v_mov_b64_e32 v[198:199], v[206:207]
	v_mov_b32_e32 v184, v0
	v_mov_b32_e32 v185, v1
	v_mov_b32_e32 v186, v2
	v_mov_b32_e32 v187, v3
	v_mov_b32_e32 v188, v4
	v_mov_b32_e32 v189, v5
	v_mov_b32_e32 v190, v6
	v_mov_b32_e32 v191, v7
.LBB0_380_ca:
	v_pk_fma_f32 v[0:1], v[44:45], v[136:137], v[36:37]
	v_lshlrev_b32_e32 v114, 16, v216
	v_pk_fma_f32 v[0:1], v[64:65], v[124:125], v[0:1]
	v_and_b32_e32 v115, 0xffff0000, v216
	v_pk_fma_f32 v[0:1], v[56:57], v[110:111], v[0:1]
	v_lshlrev_b32_e32 v112, 16, v217
	v_pk_fma_f32 v[116:117], v[60:61], v[114:115], v[0:1]
	v_pk_fma_f32 v[0:1], v[46:47], v[134:135], v[38:39]
	v_and_b32_e32 v113, 0xffff0000, v217
	v_pk_fma_f32 v[0:1], v[66:67], v[230:231], v[0:1]
	v_lshlrev_b32_e32 v222, 16, v218
	v_pk_fma_f32 v[0:1], v[58:59], v[108:109], v[0:1]
	v_and_b32_e32 v223, 0xffff0000, v218
	v_pk_fma_f32 v[118:119], v[62:63], v[112:113], v[0:1]
	v_pk_fma_f32 v[0:1], v[40:41], v[132:133], v[32:33]
	v_lshlrev_b32_e32 v216, 16, v219
	v_pk_fma_f32 v[0:1], v[48:49], v[228:229], v[0:1]
	v_and_b32_e32 v217, 0xffff0000, v219
	v_pk_fma_f32 v[0:1], v[52:53], v[226:227], v[0:1]
	s_mov_b64 s[16:17], -1
	v_pk_fma_f32 v[122:123], v[68:69], v[222:223], v[0:1]
	v_pk_fma_f32 v[0:1], v[42:43], v[126:127], v[34:35]
	s_and_b64 vcc, exec, s[8:9]
	v_pk_fma_f32 v[0:1], v[50:51], v[224:225], v[0:1]
	v_mul_f32_e32 v137, 0xbfb8aa3b, v116
	v_pk_fma_f32 v[0:1], v[54:55], v[220:221], v[0:1]
	v_mul_f32_e32 v136, 0xbfb8aa3b, v117
	v_pk_fma_f32 v[120:121], v[70:71], v[216:217], v[0:1]
	v_or_b32_e32 v0, 5, v128
	v_add_u32_e32 v218, s95, v0
	v_mul_f32_e32 v135, 0xbfb8aa3b, v118
	v_mul_f32_e32 v134, 0xbfb8aa3b, v119
	v_mul_f32_e32 v133, 0xbfb8aa3b, v122
	v_mul_f32_e32 v132, 0xbfb8aa3b, v123
	v_mul_f32_e32 v127, 0xbfb8aa3b, v120
	v_mul_f32_e32 v126, 0xbfb8aa3b, v121
	v_ashrrev_i32_e32 v219, 31, v218
	s_cbranch_vccnz .LBB0_382_ca
	v_exp_f32_e32 v3, v137
	v_lshl_add_u32 v1, v0, 2, 0
	v_add_u32_e32 v1, 0x21800, v1
	ds_read_b32 v2, v1
	v_exp_f32_e32 v1, v136
	v_add_f32_e32 v3, 1.0, v3
	v_rcp_f32_e32 v4, v3
	v_exp_f32_e32 v3, v135
	v_exp_f32_e32 v7, v134
	v_add_f32_e32 v1, 1.0, v1
	v_rcp_f32_e32 v5, v1
	v_add_f32_e32 v1, 1.0, v3
	v_rcp_f32_e32 v6, v1
	v_add_f32_e32 v1, 1.0, v7
	v_rcp_f32_e32 v7, v1
	v_exp_f32_e32 v1, v133
	v_pk_mul_f32 v[4:5], v[116:117], v[4:5]
	v_exp_f32_e32 v207, v126
	v_pk_mul_f32 v[6:7], v[118:119], v[6:7]
	v_add_f32_e32 v1, 1.0, v1
	v_pk_mul_f32 v[4:5], v[4:5], s[68:69] op_sel_hi:[1,0]
	v_pk_mul_f32 v[6:7], v[6:7], s[68:69] op_sel_hi:[1,0]
	v_rcp_f32_e32 v204, v1
	v_exp_f32_e32 v1, v127
	s_waitcnt lgkmcnt(0)
	v_pk_mul_f32 v[200:201], v[4:5], v[2:3] op_sel_hi:[1,0]
	v_pk_mul_f32 v[202:203], v[6:7], v[2:3] op_sel_hi:[1,0]
	v_exp_f32_e32 v3, v132
	v_add_f32_e32 v1, 1.0, v1
	v_rcp_f32_e32 v206, v1
	v_add_f32_e32 v1, 1.0, v207
	v_add_f32_e32 v3, 1.0, v3
	v_rcp_f32_e32 v205, v3
	v_rcp_f32_e32 v207, v1
	v_mad_u64_u32 v[0:1], s[0:1], v0, s91, v[102:103]
	v_pk_mul_f32 v[204:205], v[122:123], v[204:205]
	v_pk_mul_f32 v[206:207], v[120:121], v[206:207]
	v_pk_mul_f32 v[204:205], v[204:205], s[68:69] op_sel_hi:[1,0]
	v_pk_mul_f32 v[206:207], v[206:207], s[68:69] op_sel_hi:[1,0]
	v_pk_mul_f32 v[138:139], v[204:205], v[2:3] op_sel_hi:[1,0]
	v_pk_mul_f32 v[140:141], v[206:207], v[2:3] op_sel_hi:[1,0]
	v_cvt_pk_bf16_f32 v3, v6, v7
	v_lshlrev_b64 v[6:7], 11, v[218:219]
	v_cvt_pk_bf16_f32 v2, v4, v5
	v_cvt_pk_bf16_f32 v4, v204, v205
	v_cvt_pk_bf16_f32 v5, v206, v207
	v_lshl_add_u64 v[6:7], v[100:101], 0, v[6:7]
	global_store_dwordx4 v[6:7], v[2:5], off
	v_cvt_pk_bf16_f32 v6, v138, v139
	v_cvt_pk_bf16_f32 v7, v140, v141
	v_cvt_pk_bf16_f32 v4, v200, v201
	v_cvt_pk_bf16_f32 v5, v202, v203
	ds_write_b128 v0, v[4:7]
	v_lshlrev_b32_e32 v0, 16, v4
	v_and_b32_e32 v1, 0xffff0000, v4
	v_lshlrev_b32_e32 v2, 16, v5
	v_and_b32_e32 v3, 0xffff0000, v5
	v_lshlrev_b32_e32 v4, 16, v6
	v_and_b32_e32 v5, 0xffff0000, v6
	v_lshlrev_b32_e32 v6, 16, v7
	v_and_b32_e32 v7, 0xffff0000, v7
	v_pk_add_f32 v[6:7], v[198:199], v[6:7]
	v_pk_add_f32 v[0:1], v[192:193], v[0:1]
	v_pk_add_f32 v[2:3], v[194:195], v[2:3]
	v_pk_add_f32 v[4:5], v[196:197], v[4:5]
	s_mov_b64 s[16:17], 0
	v_mov_b64_e32 v[206:207], v[6:7]
	v_mov_b64_e32 v[204:205], v[4:5]
	v_mov_b64_e32 v[202:203], v[2:3]
	v_mov_b64_e32 v[200:201], v[0:1]
.LBB0_382_ca:
	s_andn2_b64 vcc, exec, s[16:17]
	s_cbranch_vccnz .LBB0_384_ca
	v_exp_f32_e32 v0, v137
	v_exp_f32_e32 v1, v136
	v_exp_f32_e32 v2, v135
	v_exp_f32_e32 v3, v134
	v_exp_f32_e32 v4, v133
	v_exp_f32_e32 v5, v132
	v_exp_f32_e32 v6, v127
	v_exp_f32_e32 v7, v126
	v_add_f32_e32 v0, 1.0, v0
	v_add_f32_e32 v1, 1.0, v1
	v_add_f32_e32 v2, 1.0, v2
	v_add_f32_e32 v3, 1.0, v3
	v_add_f32_e32 v4, 1.0, v4
	v_add_f32_e32 v5, 1.0, v5
	v_rcp_f32_e32 v0, v0
	v_rcp_f32_e32 v1, v1
	v_rcp_f32_e32 v2, v2
	v_rcp_f32_e32 v3, v3
	v_rcp_f32_e32 v4, v4
	v_rcp_f32_e32 v5, v5
	v_add_f32_e32 v6, 1.0, v6
	v_add_f32_e32 v7, 1.0, v7
	v_rcp_f32_e32 v6, v6
	v_rcp_f32_e32 v7, v7
	v_pk_mul_f32 v[0:1], v[116:117], v[0:1]
	v_pk_mul_f32 v[2:3], v[118:119], v[2:3]
	v_pk_mul_f32 v[4:5], v[122:123], v[4:5]
	v_pk_mul_f32 v[6:7], v[120:121], v[6:7]
	v_cvt_pk_bf16_f32 v0, v0, v1
	v_cvt_pk_bf16_f32 v1, v2, v3
	v_cvt_pk_bf16_f32 v2, v4, v5
	v_lshlrev_b64 v[4:5], 11, v[218:219]
	v_cvt_pk_bf16_f32 v3, v6, v7
	v_lshl_add_u64 v[4:5], v[104:105], 0, v[4:5]
	v_mov_b64_e32 v[206:207], v[198:199]
	global_store_dwordx4 v[4:5], v[0:3], off
	v_mov_b64_e32 v[204:205], v[196:197]
	v_mov_b64_e32 v[202:203], v[194:195]
	v_mov_b64_e32 v[200:201], v[192:193]
	v_mov_b32_e32 v0, v184
	v_mov_b32_e32 v1, v185
	v_mov_b32_e32 v2, v186
	v_mov_b32_e32 v3, v187
	v_mov_b32_e32 v4, v188
	v_mov_b32_e32 v5, v189
	v_mov_b32_e32 v6, v190
	v_mov_b32_e32 v7, v191
.LBB0_384_ca:
	v_pk_fma_f32 v[184:185], v[44:45], v[124:125], v[36:37]
	v_lshlrev_b32_e32 v118, 16, v212
	v_pk_fma_f32 v[184:185], v[64:65], v[110:111], v[184:185]
	v_and_b32_e32 v119, 0xffff0000, v212
	v_pk_fma_f32 v[184:185], v[56:57], v[114:115], v[184:185]
	v_lshlrev_b32_e32 v116, 16, v213
	v_pk_fma_f32 v[120:121], v[60:61], v[118:119], v[184:185]
	v_pk_fma_f32 v[184:185], v[46:47], v[230:231], v[38:39]
	v_and_b32_e32 v117, 0xffff0000, v213
	v_pk_fma_f32 v[184:185], v[66:67], v[108:109], v[184:185]
	v_lshlrev_b32_e32 v218, 16, v214
	v_pk_fma_f32 v[184:185], v[58:59], v[112:113], v[184:185]
	v_and_b32_e32 v219, 0xffff0000, v214
	v_pk_fma_f32 v[230:231], v[62:63], v[116:117], v[184:185]
	v_pk_fma_f32 v[184:185], v[40:41], v[228:229], v[32:33]
	v_lshlrev_b32_e32 v212, 16, v215
	v_pk_fma_f32 v[184:185], v[48:49], v[226:227], v[184:185]
	v_and_b32_e32 v213, 0xffff0000, v215
	v_pk_fma_f32 v[184:185], v[52:53], v[222:223], v[184:185]
	s_mov_b64 s[16:17], -1
	v_pk_fma_f32 v[228:229], v[68:69], v[218:219], v[184:185]
	v_pk_fma_f32 v[184:185], v[42:43], v[224:225], v[34:35]
	s_and_b64 vcc, exec, s[8:9]
	v_pk_fma_f32 v[184:185], v[50:51], v[220:221], v[184:185]
	v_mul_f32_e32 v133, 0xbfb8aa3b, v120
	v_pk_fma_f32 v[184:185], v[54:55], v[216:217], v[184:185]
	v_mul_f32_e32 v132, 0xbfb8aa3b, v121
	v_pk_fma_f32 v[224:225], v[70:71], v[212:213], v[184:185]
	v_or_b32_e32 v184, 6, v128
	v_add_u32_e32 v214, s95, v184
	v_mul_f32_e32 v127, 0xbfb8aa3b, v230
	v_mul_f32_e32 v126, 0xbfb8aa3b, v231
	v_mul_f32_e32 v125, 0xbfb8aa3b, v228
	v_mul_f32_e32 v124, 0xbfb8aa3b, v229
	v_mul_f32_e32 v123, 0xbfb8aa3b, v224
	v_mul_f32_e32 v122, 0xbfb8aa3b, v225
	v_ashrrev_i32_e32 v215, 31, v214
	s_cbranch_vccnz .LBB0_386_ca
	v_exp_f32_e32 v187, v133
	v_lshl_add_u32 v185, v184, 2, 0
	v_add_u32_e32 v185, 0x21800, v185
	ds_read_b32 v186, v185
	v_exp_f32_e32 v185, v132
	v_add_f32_e32 v187, 1.0, v187
	v_rcp_f32_e32 v188, v187
	v_exp_f32_e32 v187, v127
	v_exp_f32_e32 v191, v126
	v_add_f32_e32 v185, 1.0, v185
	v_rcp_f32_e32 v189, v185
	v_add_f32_e32 v185, 1.0, v187
	v_rcp_f32_e32 v190, v185
	v_add_f32_e32 v185, 1.0, v191
	v_rcp_f32_e32 v191, v185
	v_exp_f32_e32 v185, v125
	v_pk_mul_f32 v[188:189], v[120:121], v[188:189]
	v_exp_f32_e32 v199, v122
	v_pk_mul_f32 v[190:191], v[230:231], v[190:191]
	v_add_f32_e32 v185, 1.0, v185
	v_pk_mul_f32 v[188:189], v[188:189], s[68:69] op_sel_hi:[1,0]
	v_pk_mul_f32 v[190:191], v[190:191], s[68:69] op_sel_hi:[1,0]
	v_rcp_f32_e32 v196, v185
	v_exp_f32_e32 v185, v123
	s_waitcnt lgkmcnt(0)
	v_pk_mul_f32 v[192:193], v[188:189], v[186:187] op_sel_hi:[1,0]
	v_pk_mul_f32 v[194:195], v[190:191], v[186:187] op_sel_hi:[1,0]
	v_exp_f32_e32 v187, v124
	v_add_f32_e32 v185, 1.0, v185
	v_rcp_f32_e32 v198, v185
	v_add_f32_e32 v185, 1.0, v199
	v_add_f32_e32 v187, 1.0, v187
	v_rcp_f32_e32 v197, v187
	v_rcp_f32_e32 v199, v185
	v_mad_u64_u32 v[184:185], s[0:1], v184, s91, v[102:103]
	v_pk_mul_f32 v[196:197], v[228:229], v[196:197]
	v_pk_mul_f32 v[198:199], v[224:225], v[198:199]
	v_pk_mul_f32 v[196:197], v[196:197], s[68:69] op_sel_hi:[1,0]
	v_pk_mul_f32 v[198:199], v[198:199], s[68:69] op_sel_hi:[1,0]
	v_pk_mul_f32 v[134:135], v[196:197], v[186:187] op_sel_hi:[1,0]
	v_pk_mul_f32 v[136:137], v[198:199], v[186:187] op_sel_hi:[1,0]
	v_cvt_pk_bf16_f32 v187, v190, v191
	v_lshlrev_b64 v[190:191], 11, v[214:215]
	v_cvt_pk_bf16_f32 v186, v188, v189
	v_cvt_pk_bf16_f32 v188, v196, v197
	v_cvt_pk_bf16_f32 v189, v198, v199
	v_lshl_add_u64 v[190:191], v[100:101], 0, v[190:191]
	global_store_dwordx4 v[190:191], v[186:189], off
	v_cvt_pk_bf16_f32 v190, v134, v135
	v_cvt_pk_bf16_f32 v191, v136, v137
	v_cvt_pk_bf16_f32 v188, v192, v193
	v_cvt_pk_bf16_f32 v189, v194, v195
	ds_write_b128 v184, v[188:191]
	v_lshlrev_b32_e32 v184, 16, v188
	v_and_b32_e32 v185, 0xffff0000, v188
	v_lshlrev_b32_e32 v186, 16, v189
	v_and_b32_e32 v187, 0xffff0000, v189
	v_lshlrev_b32_e32 v188, 16, v190
	v_and_b32_e32 v189, 0xffff0000, v190
	v_lshlrev_b32_e32 v190, 16, v191
	v_and_b32_e32 v191, 0xffff0000, v191
	v_pk_add_f32 v[190:191], v[206:207], v[190:191]
	v_pk_add_f32 v[184:185], v[200:201], v[184:185]
	v_pk_add_f32 v[186:187], v[202:203], v[186:187]
	v_pk_add_f32 v[188:189], v[204:205], v[188:189]
	s_mov_b64 s[16:17], 0
	v_mov_b64_e32 v[198:199], v[190:191]
	v_mov_b64_e32 v[196:197], v[188:189]
	v_mov_b64_e32 v[194:195], v[186:187]
	v_mov_b64_e32 v[192:193], v[184:185]
.LBB0_386_ca:
	s_andn2_b64 vcc, exec, s[16:17]
	s_cbranch_vccnz .LBB0_388_ca
	v_exp_f32_e32 v184, v133
	v_exp_f32_e32 v185, v132
	v_exp_f32_e32 v186, v127
	v_exp_f32_e32 v187, v126
	v_exp_f32_e32 v188, v125
	v_exp_f32_e32 v189, v124
	v_exp_f32_e32 v190, v123
	v_exp_f32_e32 v191, v122
	v_add_f32_e32 v184, 1.0, v184
	v_add_f32_e32 v185, 1.0, v185
	v_add_f32_e32 v186, 1.0, v186
	v_add_f32_e32 v187, 1.0, v187
	v_add_f32_e32 v188, 1.0, v188
	v_add_f32_e32 v189, 1.0, v189
	v_rcp_f32_e32 v184, v184
	v_rcp_f32_e32 v185, v185
	v_rcp_f32_e32 v186, v186
	v_rcp_f32_e32 v187, v187
	v_rcp_f32_e32 v188, v188
	v_rcp_f32_e32 v189, v189
	v_add_f32_e32 v190, 1.0, v190
	v_add_f32_e32 v191, 1.0, v191
	v_rcp_f32_e32 v190, v190
	v_rcp_f32_e32 v191, v191
	v_pk_mul_f32 v[184:185], v[120:121], v[184:185]
	v_pk_mul_f32 v[186:187], v[230:231], v[186:187]
	v_pk_mul_f32 v[188:189], v[228:229], v[188:189]
	v_pk_mul_f32 v[190:191], v[224:225], v[190:191]
	v_cvt_pk_bf16_f32 v184, v184, v185
	v_cvt_pk_bf16_f32 v185, v186, v187
	v_cvt_pk_bf16_f32 v186, v188, v189
	v_lshlrev_b64 v[188:189], 11, v[214:215]
	v_cvt_pk_bf16_f32 v187, v190, v191
	v_lshl_add_u64 v[188:189], v[104:105], 0, v[188:189]
	v_mov_b64_e32 v[192:193], v[200:201]
	global_store_dwordx4 v[188:189], v[184:187], off
	v_mov_b64_e32 v[194:195], v[202:203]
	v_mov_b64_e32 v[196:197], v[204:205]
	v_mov_b64_e32 v[198:199], v[206:207]
	v_mov_b32_e32 v184, v0
	v_mov_b32_e32 v185, v1
	v_mov_b32_e32 v186, v2
	v_mov_b32_e32 v187, v3
	v_mov_b32_e32 v188, v4
	v_mov_b32_e32 v189, v5
	v_mov_b32_e32 v190, v6
	v_mov_b32_e32 v191, v7
.LBB0_388_ca:
	v_pk_fma_f32 v[0:1], v[44:45], v[110:111], v[36:37]
	v_lshlrev_b32_e32 v2, 16, v208
	v_pk_fma_f32 v[0:1], v[64:65], v[114:115], v[0:1]
	v_and_b32_e32 v3, 0xffff0000, v208
	v_pk_fma_f32 v[0:1], v[56:57], v[118:119], v[0:1]
	s_mov_b64 s[16:17], -1
	v_pk_fma_f32 v[214:215], v[60:61], v[2:3], v[0:1]
	v_pk_fma_f32 v[0:1], v[46:47], v[108:109], v[38:39]
	v_lshlrev_b32_e32 v2, 16, v209
	v_pk_fma_f32 v[0:1], v[66:67], v[112:113], v[0:1]
	v_and_b32_e32 v3, 0xffff0000, v209
	v_pk_fma_f32 v[0:1], v[58:59], v[116:117], v[0:1]
	s_and_b64 vcc, exec, s[8:9]
	v_pk_fma_f32 v[224:225], v[62:63], v[2:3], v[0:1]
	v_pk_fma_f32 v[0:1], v[40:41], v[226:227], v[32:33]
	v_lshlrev_b32_e32 v2, 16, v210
	v_pk_fma_f32 v[0:1], v[48:49], v[222:223], v[0:1]
	v_and_b32_e32 v3, 0xffff0000, v210
	v_pk_fma_f32 v[0:1], v[52:53], v[218:219], v[0:1]
	v_mul_f32_e32 v223, 0xbfb8aa3b, v214
	v_pk_fma_f32 v[218:219], v[68:69], v[2:3], v[0:1]
	v_pk_fma_f32 v[0:1], v[42:43], v[220:221], v[34:35]
	v_lshlrev_b32_e32 v2, 16, v211
	v_pk_fma_f32 v[0:1], v[50:51], v[216:217], v[0:1]
	v_and_b32_e32 v3, 0xffff0000, v211
	v_pk_fma_f32 v[0:1], v[54:55], v[212:213], v[0:1]
	v_mul_f32_e32 v222, 0xbfb8aa3b, v215
	v_pk_fma_f32 v[210:211], v[70:71], v[2:3], v[0:1]
	v_or_b32_e32 v0, 7, v128
	v_add_u32_e32 v208, s95, v0
	v_mul_f32_e32 v221, 0xbfb8aa3b, v224
	v_mul_f32_e32 v220, 0xbfb8aa3b, v225
	v_mul_f32_e32 v217, 0xbfb8aa3b, v218
	v_mul_f32_e32 v216, 0xbfb8aa3b, v219
	v_mul_f32_e32 v213, 0xbfb8aa3b, v210
	v_mul_f32_e32 v212, 0xbfb8aa3b, v211
	v_ashrrev_i32_e32 v209, 31, v208
	s_cbranch_vccnz .LBB0_390_ca
	v_exp_f32_e32 v3, v223
	v_lshl_add_u32 v1, v0, 2, 0
	v_add_u32_e32 v1, 0x21800, v1
	ds_read_b32 v2, v1
	v_exp_f32_e32 v1, v222
	v_add_f32_e32 v3, 1.0, v3
	v_rcp_f32_e32 v4, v3
	v_exp_f32_e32 v3, v221
	v_exp_f32_e32 v7, v220
	v_add_f32_e32 v1, 1.0, v1
	v_rcp_f32_e32 v5, v1
	v_add_f32_e32 v1, 1.0, v3
	v_rcp_f32_e32 v6, v1
	v_add_f32_e32 v1, 1.0, v7
	v_rcp_f32_e32 v7, v1
	v_exp_f32_e32 v1, v217
	v_pk_mul_f32 v[4:5], v[214:215], v[4:5]
	v_exp_f32_e32 v207, v212
	v_pk_mul_f32 v[6:7], v[224:225], v[6:7]
	v_add_f32_e32 v1, 1.0, v1
	v_pk_mul_f32 v[4:5], v[4:5], s[68:69] op_sel_hi:[1,0]
	v_pk_mul_f32 v[6:7], v[6:7], s[68:69] op_sel_hi:[1,0]
	v_rcp_f32_e32 v204, v1
	v_exp_f32_e32 v1, v213
	s_waitcnt lgkmcnt(0)
	v_pk_mul_f32 v[200:201], v[4:5], v[2:3] op_sel_hi:[1,0]
	v_pk_mul_f32 v[202:203], v[6:7], v[2:3] op_sel_hi:[1,0]
	v_exp_f32_e32 v3, v216
	v_add_f32_e32 v1, 1.0, v1
	v_rcp_f32_e32 v206, v1
	v_add_f32_e32 v1, 1.0, v207
	v_add_f32_e32 v3, 1.0, v3
	v_rcp_f32_e32 v205, v3
	v_rcp_f32_e32 v207, v1
	v_mad_u64_u32 v[0:1], s[0:1], v0, s91, v[102:103]
	v_pk_mul_f32 v[204:205], v[218:219], v[204:205]
	v_pk_mul_f32 v[206:207], v[210:211], v[206:207]
	v_pk_mul_f32 v[204:205], v[204:205], s[68:69] op_sel_hi:[1,0]
	v_pk_mul_f32 v[206:207], v[206:207], s[68:69] op_sel_hi:[1,0]
	v_pk_mul_f32 v[226:227], v[204:205], v[2:3] op_sel_hi:[1,0]
	v_pk_mul_f32 v[228:229], v[206:207], v[2:3] op_sel_hi:[1,0]
	v_cvt_pk_bf16_f32 v3, v6, v7
	v_lshlrev_b64 v[6:7], 11, v[208:209]
	v_cvt_pk_bf16_f32 v2, v4, v5
	v_cvt_pk_bf16_f32 v4, v204, v205
	v_cvt_pk_bf16_f32 v5, v206, v207
	v_lshl_add_u64 v[6:7], v[100:101], 0, v[6:7]
	global_store_dwordx4 v[6:7], v[2:5], off
	v_cvt_pk_bf16_f32 v6, v226, v227
	v_cvt_pk_bf16_f32 v7, v228, v229
	v_cvt_pk_bf16_f32 v4, v200, v201
	v_cvt_pk_bf16_f32 v5, v202, v203
	ds_write_b128 v0, v[4:7]
	v_lshlrev_b32_e32 v0, 16, v4
	v_and_b32_e32 v1, 0xffff0000, v4
	v_lshlrev_b32_e32 v2, 16, v5
	v_and_b32_e32 v3, 0xffff0000, v5
	v_lshlrev_b32_e32 v4, 16, v6
	v_and_b32_e32 v5, 0xffff0000, v6
	v_lshlrev_b32_e32 v6, 16, v7
	v_and_b32_e32 v7, 0xffff0000, v7
	v_pk_add_f32 v[6:7], v[198:199], v[6:7]
	v_pk_add_f32 v[0:1], v[192:193], v[0:1]
	v_pk_add_f32 v[2:3], v[194:195], v[2:3]
	v_pk_add_f32 v[4:5], v[196:197], v[4:5]
	s_mov_b64 s[16:17], 0
	v_mov_b64_e32 v[206:207], v[6:7]
	v_mov_b64_e32 v[204:205], v[4:5]
	v_mov_b64_e32 v[202:203], v[2:3]
	v_mov_b64_e32 v[200:201], v[0:1]
.LBB0_390_ca:
	s_andn2_b64 vcc, exec, s[16:17]
	s_cbranch_vccnz .Lconv_h1
	v_exp_f32_e32 v0, v223
	v_exp_f32_e32 v1, v222
	v_exp_f32_e32 v2, v221
	v_exp_f32_e32 v3, v220
	v_exp_f32_e32 v4, v217
	v_exp_f32_e32 v5, v216
	v_exp_f32_e32 v6, v213
	v_exp_f32_e32 v7, v212
	v_add_f32_e32 v0, 1.0, v0
	v_add_f32_e32 v1, 1.0, v1
	v_add_f32_e32 v2, 1.0, v2
	v_add_f32_e32 v3, 1.0, v3
	v_add_f32_e32 v4, 1.0, v4
	v_add_f32_e32 v5, 1.0, v5
	v_rcp_f32_e32 v0, v0
	v_rcp_f32_e32 v1, v1
	v_rcp_f32_e32 v2, v2
	v_rcp_f32_e32 v3, v3
	v_rcp_f32_e32 v4, v4
	v_rcp_f32_e32 v5, v5
	v_add_f32_e32 v6, 1.0, v6
	v_add_f32_e32 v7, 1.0, v7
	v_rcp_f32_e32 v6, v6
	v_rcp_f32_e32 v7, v7
	v_pk_mul_f32 v[0:1], v[214:215], v[0:1]
	v_pk_mul_f32 v[2:3], v[224:225], v[2:3]
	v_pk_mul_f32 v[4:5], v[218:219], v[4:5]
	v_pk_mul_f32 v[6:7], v[210:211], v[6:7]
	v_cvt_pk_bf16_f32 v0, v0, v1
	v_cvt_pk_bf16_f32 v1, v2, v3
	v_cvt_pk_bf16_f32 v2, v4, v5
	v_lshlrev_b64 v[4:5], 11, v[208:209]
	v_cvt_pk_bf16_f32 v3, v6, v7
	v_lshl_add_u64 v[4:5], v[104:105], 0, v[4:5]
	v_mov_b64_e32 v[206:207], v[198:199]
	global_store_dwordx4 v[4:5], v[0:3], off
	v_mov_b64_e32 v[204:205], v[196:197]
	v_mov_b64_e32 v[202:203], v[194:195]
	v_mov_b64_e32 v[200:201], v[192:193]
	v_mov_b32_e32 v0, v184
	v_mov_b32_e32 v1, v185
	v_mov_b32_e32 v2, v186
	v_mov_b32_e32 v3, v187
	v_mov_b32_e32 v4, v188
	v_mov_b32_e32 v5, v189
	v_mov_b32_e32 v6, v190
	v_mov_b32_e32 v7, v191
	s_branch .Lconv_h1
.Lconv_h1:
	s_mov_b32 s0, 8
